# cache policy: FFN intermediate (hid) stores sc1 nt (write-through, non-temporal) instead of sc1 only
# baseline (speedup 1.0000x reference)
; __device__ __forceinline__ float silu_f(float x) { return x * __builtin_amdgcn_rcpf(1.0f + __builtin_amdgcn_exp2f(-1.4426950408889634f * x)); }
;     __device__ __forceinline__ void operator()(const i32x4 (&acc)[2][2][4][2], const pg8::Unit& u, int wr, int wc, int fr_, int fq_, int tid) {
;     ...
;         const int row0 = u.pm * 256 + wr * 64 + fr, col0 = u.pn * 128 + wc * 32 + 8 * fq;
;         const float* cp = cmax + u.pn * 256 + wc * 32 + 8 * fq;
;         f32x4 cs[2][2];
;         cs[0][0] = *(const f32x4*)(cp) * (1.0f / 127.0f); cs[0][1] = *(const f32x4*)(cp + 4) * (1.0f / 127.0f);
;         cs[1][0] = *(const f32x4*)(cp + 128) * (1.0f / 127.0f); cs[1][1] = *(const f32x4*)(cp + 132) * (1.0f / 127.0f);
; #pragma unroll
;         for (int ai = 0; ai < 2; ++ai)
; #pragma unroll
;             for (int m = 0; m < 4; ++m) {
;                 const int row = row0 + ai * 128 + m * 16;
;                 const float rs = rsl[wr * 64 + fr + ai * 128 + m * 16];
;                 f32x4 h[2];
; #pragma unroll
;                 for (int n = 0; n < 2; ++n) {
; #pragma unroll
;                     for (int i = 0; i < 4; ++i) { const float g = (float)acc[ai][0][m][n][i] * (rs * cs[0][n][i]), up = (float)acc[ai][1][m][n][i] * (rs * cs[1][n][i]); h[n][i] = silu_f(g) * up; } }
;                 *(u32x4*)(H + ((size_t)(u.pm * (DFF / 64) + (col0 >> 6)) * 256 + (size_t)(row & 255)) * 64 + (col0 & 63)) = pack8bf(h[0], h[1]);
.LBB0_166:
	s_mul_i32 s13, s20, 0x58
	v_lshrrev_b32_e32 v175, 4, v195
	v_and_b32_e32 v174, 15, v195
	s_lshr_b32 s22, s21, 2
	s_lshl_b32 s22, s22, 10
	s_lshl_b32 s23, s41, 3
	s_add_i32 s22, s22, s23
	s_add_i32 s22, s22, 0x21000
	v_lshlrev_b32_e32 v176, 4, v175
	v_lshl_add_u32 v175, v175, 5, s22
	ds_read_b128 v[216:219], v175
	ds_read_b128 v[220:223], v175 offset:16
	ds_read_b128 v[224:227], v175 offset:128
	ds_read_b128 v[228:231], v175 offset:144
	v_add_u32_e32 v177, s40, v174
	v_lshl_add_u32 v174, v174, 2, s47
	ds_read_b32 v232, v174
	ds_read_b32 v234, v174 offset:64
	ds_read_b32 v236, v174 offset:128
	ds_read_b32 v238, v174 offset:192
	ds_read_b32 v240, v174 offset:512
	ds_read_b32 v242, v174 offset:576
	ds_read_b32 v244, v174 offset:640
	ds_read_b32 v246, v174 offset:704
	v_lshl_add_u32 v176, v177, 7, v176
	s_lshl_b32 s22, s21, 1
	s_add_i32 s13, s13, s22
	s_lshr_b32 s22, s41, 6
	s_add_i32 s13, s13, s22
	s_and_b32 s22, s41, 32
	s_lshl_b32 s22, s22, 1
	v_add_u32_e32 v176, s22, v176
	s_lshl_b32 s13, s13, 15
	s_add_u32 s20, s8, s13
	s_addc_u32 s21, s9, 0
	v_cvt_f32_i32_e32 v126, v126
	v_cvt_f32_i32_e32 v127, v127
	v_cvt_f32_i32_e32 v128, v128
	v_cvt_f32_i32_e32 v129, v129
	v_cvt_f32_i32_e32 v122, v122
	v_cvt_f32_i32_e32 v123, v123
	v_cvt_f32_i32_e32 v124, v124
	v_cvt_f32_i32_e32 v125, v125
	v_cvt_f32_i32_e32 v118, v118
	v_cvt_f32_i32_e32 v119, v119
	v_cvt_f32_i32_e32 v120, v120
	v_cvt_f32_i32_e32 v121, v121
	v_cvt_f32_i32_e32 v114, v114
	v_cvt_f32_i32_e32 v115, v115
	v_cvt_f32_i32_e32 v116, v116
	v_cvt_f32_i32_e32 v117, v117
	v_cvt_f32_i32_e32 v110, v110
	v_cvt_f32_i32_e32 v111, v111
	v_cvt_f32_i32_e32 v112, v112
	v_cvt_f32_i32_e32 v113, v113
	v_cvt_f32_i32_e32 v106, v106
	v_cvt_f32_i32_e32 v107, v107
	v_cvt_f32_i32_e32 v108, v108
	v_cvt_f32_i32_e32 v109, v109
	v_cvt_f32_i32_e32 v102, v102
	v_cvt_f32_i32_e32 v103, v103
	v_cvt_f32_i32_e32 v104, v104
	v_cvt_f32_i32_e32 v105, v105
	v_cvt_f32_i32_e32 v98, v98
	v_cvt_f32_i32_e32 v99, v99
	v_cvt_f32_i32_e32 v100, v100
	v_cvt_f32_i32_e32 v101, v101
	s_waitcnt lgkmcnt(0)
	v_mul_f32_e32 v233, v232, v232
	v_mul_f32_e32 v235, v234, v234
	v_mul_f32_e32 v237, v236, v236
	v_mul_f32_e32 v239, v238, v238
	v_mul_f32_e32 v241, v240, v240
	v_mul_f32_e32 v243, v242, v242
	v_mul_f32_e32 v245, v244, v244
	v_mul_f32_e32 v247, v246, v246
	v_rcp_f32_e32 v233, v233
	v_rcp_f32_e32 v235, v235
	v_rcp_f32_e32 v237, v237
	v_rcp_f32_e32 v239, v239
	v_rcp_f32_e32 v241, v241
	v_rcp_f32_e32 v243, v243
	v_rcp_f32_e32 v245, v245
	v_rcp_f32_e32 v247, v247
	v_mul_f32_e32 v232, 0xbfb8aa3b, v232
	v_mul_f32_e32 v234, 0xbfb8aa3b, v234
	v_mul_f32_e32 v236, 0xbfb8aa3b, v236
	v_mul_f32_e32 v238, 0xbfb8aa3b, v238
	v_mul_f32_e32 v240, 0xbfb8aa3b, v240
	v_mul_f32_e32 v242, 0xbfb8aa3b, v242
	v_mul_f32_e32 v244, 0xbfb8aa3b, v244
	v_mul_f32_e32 v246, 0xbfb8aa3b, v246
	v_cvt_f32_i32_e32 v94, v94
	v_cvt_f32_i32_e32 v95, v95
	v_cvt_f32_i32_e32 v96, v96
	v_cvt_f32_i32_e32 v97, v97
	v_cvt_f32_i32_e32 v90, v90
	v_cvt_f32_i32_e32 v91, v91
	v_cvt_f32_i32_e32 v92, v92
	v_cvt_f32_i32_e32 v93, v93
	v_cvt_f32_i32_e32 v86, v86
	v_cvt_f32_i32_e32 v87, v87
	v_cvt_f32_i32_e32 v88, v88
	v_cvt_f32_i32_e32 v89, v89
	v_cvt_f32_i32_e32 v82, v82
	v_cvt_f32_i32_e32 v83, v83
	v_cvt_f32_i32_e32 v84, v84
	v_cvt_f32_i32_e32 v85, v85
	v_pk_mul_f32 v[126:127], v[126:127], v[216:217]
	v_pk_mul_f32 v[128:129], v[128:129], v[218:219]
	v_pk_mul_f32 v[122:123], v[122:123], v[224:225]
	v_pk_mul_f32 v[124:125], v[124:125], v[226:227]
	v_pk_mul_f32 v[248:249], v[126:127], v[232:233] op_sel_hi:[1,0]
	v_pk_mul_f32 v[250:251], v[128:129], v[232:233] op_sel_hi:[1,0]
	v_pk_mul_f32 v[126:127], v[126:127], v[122:123]
	v_exp_f32_e32 v248, v248
	v_exp_f32_e32 v249, v249
	v_exp_f32_e32 v250, v250
	v_exp_f32_e32 v251, v251
	v_pk_mul_f32 v[128:129], v[128:129], v[124:125]
	v_pk_fma_f32 v[248:249], v[248:249], v[232:233], v[232:233] op_sel:[0,1,1] op_sel_hi:[1,1,1]
	v_pk_fma_f32 v[250:251], v[250:251], v[232:233], v[232:233] op_sel:[0,1,1] op_sel_hi:[1,1,1]
	v_rcp_f32_e32 v248, v248
	v_rcp_f32_e32 v249, v249
	v_rcp_f32_e32 v250, v250
	v_rcp_f32_e32 v251, v251
	v_pk_mul_f32 v[126:127], v[126:127], v[248:249]
	v_pk_mul_f32 v[128:129], v[128:129], v[250:251]
	v_cvt_pk_bf16_f32 v122, v126, v127
	v_cvt_pk_bf16_f32 v123, v128, v129
	v_pk_mul_f32 v[118:119], v[118:119], v[220:221]
	v_pk_mul_f32 v[120:121], v[120:121], v[222:223]
	v_pk_mul_f32 v[114:115], v[114:115], v[228:229]
	v_pk_mul_f32 v[116:117], v[116:117], v[230:231]
	v_pk_mul_f32 v[248:249], v[118:119], v[232:233] op_sel_hi:[1,0]
	v_pk_mul_f32 v[250:251], v[120:121], v[232:233] op_sel_hi:[1,0]
	v_pk_mul_f32 v[118:119], v[118:119], v[114:115]
	v_exp_f32_e32 v248, v248
	v_exp_f32_e32 v249, v249
	v_exp_f32_e32 v250, v250
	v_exp_f32_e32 v251, v251
	v_pk_mul_f32 v[120:121], v[120:121], v[116:117]
	v_pk_fma_f32 v[248:249], v[248:249], v[232:233], v[232:233] op_sel:[0,1,1] op_sel_hi:[1,1,1]
	v_pk_fma_f32 v[250:251], v[250:251], v[232:233], v[232:233] op_sel:[0,1,1] op_sel_hi:[1,1,1]
	v_rcp_f32_e32 v248, v248
	v_rcp_f32_e32 v249, v249
	v_rcp_f32_e32 v250, v250
	v_rcp_f32_e32 v251, v251
	v_pk_mul_f32 v[118:119], v[118:119], v[248:249]
	v_pk_mul_f32 v[120:121], v[120:121], v[250:251]
	v_cvt_pk_bf16_f32 v124, v118, v119
	v_cvt_pk_bf16_f32 v125, v120, v121
	s_mov_b64 s[22:23], s[20:21]
	global_store_dwordx4 v176, v[122:125], s[22:23] sc1 nt
	v_cvt_f32_i32_e32 v78, v78
	v_cvt_f32_i32_e32 v79, v79
	v_cvt_f32_i32_e32 v80, v80
	v_cvt_f32_i32_e32 v81, v81
	v_cvt_f32_i32_e32 v74, v74
	v_cvt_f32_i32_e32 v75, v75
	v_cvt_f32_i32_e32 v76, v76
	v_cvt_f32_i32_e32 v77, v77
	v_cvt_f32_i32_e32 v70, v70
	v_cvt_f32_i32_e32 v71, v71
	v_cvt_f32_i32_e32 v72, v72
; __device__ __forceinline__ float silu_f(float x) { return x * __builtin_amdgcn_rcpf(1.0f + __builtin_amdgcn_exp2f(-1.4426950408889634f * x)); }
;     __device__ __forceinline__ void operator()(const i32x4 (&acc)[2][2][4][2], const pg8::Unit& u, int wr, int wc, int fr_, int fq_, int tid) {
;     ...
;         for (int ai = 0; ai < 2; ++ai)
; #pragma unroll
;             for (int m = 0; m < 4; ++m) {
;                 const int row = row0 + ai * 128 + m * 16;
;                 const float rs = rsl[wr * 64 + fr + ai * 128 + m * 16];
;                 f32x4 h[2];
; #pragma unroll
;                 for (int n = 0; n < 2; ++n) {
; #pragma unroll
;                     for (int i = 0; i < 4; ++i) { const float g = (float)acc[ai][0][m][n][i] * (rs * cs[0][n][i]), up = (float)acc[ai][1][m][n][i] * (rs * cs[1][n][i]); h[n][i] = silu_f(g) * up; } }
;                 *(u32x4*)(H + ((size_t)(u.pm * (DFF / 64) + (col0 >> 6)) * 256 + (size_t)(row & 255)) * 64 + (col0 & 63)) = pack8bf(h[0], h[1]);
	v_cvt_f32_i32_e32 v73, v73
	v_cvt_f32_i32_e32 v66, v66
	v_cvt_f32_i32_e32 v67, v67
	v_cvt_f32_i32_e32 v68, v68
	v_cvt_f32_i32_e32 v69, v69
	v_pk_mul_f32 v[110:111], v[110:111], v[216:217]
	v_pk_mul_f32 v[112:113], v[112:113], v[218:219]
	v_pk_mul_f32 v[106:107], v[106:107], v[224:225]
	v_pk_mul_f32 v[108:109], v[108:109], v[226:227]
	v_pk_mul_f32 v[248:249], v[110:111], v[234:235] op_sel_hi:[1,0]
	v_pk_mul_f32 v[250:251], v[112:113], v[234:235] op_sel_hi:[1,0]
	v_pk_mul_f32 v[110:111], v[110:111], v[106:107]
	v_exp_f32_e32 v248, v248
	v_exp_f32_e32 v249, v249
	v_exp_f32_e32 v250, v250
	v_exp_f32_e32 v251, v251
	v_pk_mul_f32 v[112:113], v[112:113], v[108:109]
	v_pk_fma_f32 v[248:249], v[248:249], v[234:235], v[234:235] op_sel:[0,1,1] op_sel_hi:[1,1,1]
	v_pk_fma_f32 v[250:251], v[250:251], v[234:235], v[234:235] op_sel:[0,1,1] op_sel_hi:[1,1,1]
	v_rcp_f32_e32 v248, v248
	v_rcp_f32_e32 v249, v249
	v_rcp_f32_e32 v250, v250
	v_rcp_f32_e32 v251, v251
	v_pk_mul_f32 v[110:111], v[110:111], v[248:249]
	v_pk_mul_f32 v[112:113], v[112:113], v[250:251]
	v_cvt_pk_bf16_f32 v106, v110, v111
	v_cvt_pk_bf16_f32 v107, v112, v113
	v_pk_mul_f32 v[102:103], v[102:103], v[220:221]
	v_pk_mul_f32 v[104:105], v[104:105], v[222:223]
	v_pk_mul_f32 v[98:99], v[98:99], v[228:229]
	v_pk_mul_f32 v[100:101], v[100:101], v[230:231]
	v_pk_mul_f32 v[248:249], v[102:103], v[234:235] op_sel_hi:[1,0]
	v_pk_mul_f32 v[250:251], v[104:105], v[234:235] op_sel_hi:[1,0]
	v_pk_mul_f32 v[102:103], v[102:103], v[98:99]
	v_exp_f32_e32 v248, v248
	v_exp_f32_e32 v249, v249
	v_exp_f32_e32 v250, v250
	v_exp_f32_e32 v251, v251
	v_pk_mul_f32 v[104:105], v[104:105], v[100:101]
	v_pk_fma_f32 v[248:249], v[248:249], v[234:235], v[234:235] op_sel:[0,1,1] op_sel_hi:[1,1,1]
	v_pk_fma_f32 v[250:251], v[250:251], v[234:235], v[234:235] op_sel:[0,1,1] op_sel_hi:[1,1,1]
	v_rcp_f32_e32 v248, v248
	v_rcp_f32_e32 v249, v249
	v_rcp_f32_e32 v250, v250
	v_rcp_f32_e32 v251, v251
	v_pk_mul_f32 v[102:103], v[102:103], v[248:249]
	v_pk_mul_f32 v[104:105], v[104:105], v[250:251]
	v_cvt_pk_bf16_f32 v108, v102, v103
	v_cvt_pk_bf16_f32 v109, v104, v105
	global_store_dwordx4 v176, v[106:109], s[22:23] offset:2048 sc1 nt
	v_cvt_f32_i32_e32 v62, v62
	v_cvt_f32_i32_e32 v63, v63
	v_cvt_f32_i32_e32 v64, v64
	v_cvt_f32_i32_e32 v65, v65
	v_cvt_f32_i32_e32 v58, v58
	v_cvt_f32_i32_e32 v59, v59
	v_cvt_f32_i32_e32 v60, v60
	v_cvt_f32_i32_e32 v61, v61
	v_cvt_f32_i32_e32 v54, v54
	v_cvt_f32_i32_e32 v55, v55
	v_cvt_f32_i32_e32 v56, v56
	v_cvt_f32_i32_e32 v57, v57
	v_cvt_f32_i32_e32 v50, v50
	v_cvt_f32_i32_e32 v51, v51
	v_cvt_f32_i32_e32 v52, v52
	v_cvt_f32_i32_e32 v53, v53
	v_pk_mul_f32 v[94:95], v[94:95], v[216:217]
	v_pk_mul_f32 v[96:97], v[96:97], v[218:219]
	v_pk_mul_f32 v[90:91], v[90:91], v[224:225]
	v_pk_mul_f32 v[92:93], v[92:93], v[226:227]
	v_pk_mul_f32 v[248:249], v[94:95], v[236:237] op_sel_hi:[1,0]
	v_pk_mul_f32 v[250:251], v[96:97], v[236:237] op_sel_hi:[1,0]
	v_pk_mul_f32 v[94:95], v[94:95], v[90:91]
	v_exp_f32_e32 v248, v248
	v_exp_f32_e32 v249, v249
	v_exp_f32_e32 v250, v250
	v_exp_f32_e32 v251, v251
	v_pk_mul_f32 v[96:97], v[96:97], v[92:93]
	v_pk_fma_f32 v[248:249], v[248:249], v[236:237], v[236:237] op_sel:[0,1,1] op_sel_hi:[1,1,1]
	v_pk_fma_f32 v[250:251], v[250:251], v[236:237], v[236:237] op_sel:[0,1,1] op_sel_hi:[1,1,1]
	v_rcp_f32_e32 v248, v248
	v_rcp_f32_e32 v249, v249
	v_rcp_f32_e32 v250, v250
	v_rcp_f32_e32 v251, v251
	v_pk_mul_f32 v[94:95], v[94:95], v[248:249]
	v_pk_mul_f32 v[96:97], v[96:97], v[250:251]
	v_cvt_pk_bf16_f32 v90, v94, v95
	v_cvt_pk_bf16_f32 v91, v96, v97
	v_pk_mul_f32 v[86:87], v[86:87], v[220:221]
	v_pk_mul_f32 v[88:89], v[88:89], v[222:223]
	v_pk_mul_f32 v[82:83], v[82:83], v[228:229]
	v_pk_mul_f32 v[84:85], v[84:85], v[230:231]
	v_pk_mul_f32 v[248:249], v[86:87], v[236:237] op_sel_hi:[1,0]
	v_pk_mul_f32 v[250:251], v[88:89], v[236:237] op_sel_hi:[1,0]
	v_pk_mul_f32 v[86:87], v[86:87], v[82:83]
	v_exp_f32_e32 v248, v248
	v_exp_f32_e32 v249, v249
	v_exp_f32_e32 v250, v250
	v_exp_f32_e32 v251, v251
	v_pk_mul_f32 v[88:89], v[88:89], v[84:85]
	v_pk_fma_f32 v[248:249], v[248:249], v[236:237], v[236:237] op_sel:[0,1,1] op_sel_hi:[1,1,1]
	v_pk_fma_f32 v[250:251], v[250:251], v[236:237], v[236:237] op_sel:[0,1,1] op_sel_hi:[1,1,1]
	v_rcp_f32_e32 v248, v248
	v_rcp_f32_e32 v249, v249
	v_rcp_f32_e32 v250, v250
	v_rcp_f32_e32 v251, v251
	v_pk_mul_f32 v[86:87], v[86:87], v[248:249]
	v_pk_mul_f32 v[88:89], v[88:89], v[250:251]
	v_cvt_pk_bf16_f32 v92, v86, v87
	v_cvt_pk_bf16_f32 v93, v88, v89
	s_add_u32 s22, s20, 0x1000
	s_addc_u32 s23, s21, 0
	global_store_dwordx4 v176, v[90:93], s[22:23] sc1 nt
	v_cvt_f32_i32_e32 v46, v46
	v_cvt_f32_i32_e32 v47, v47
	v_cvt_f32_i32_e32 v48, v48
	v_cvt_f32_i32_e32 v49, v49
	v_cvt_f32_i32_e32 v42, v42
	v_cvt_f32_i32_e32 v43, v43
	v_cvt_f32_i32_e32 v44, v44
	v_cvt_f32_i32_e32 v45, v45
	v_cvt_f32_i32_e32 v38, v38
	v_cvt_f32_i32_e32 v39, v39
	v_cvt_f32_i32_e32 v40, v40
	v_cvt_f32_i32_e32 v41, v41
	v_cvt_f32_i32_e32 v34, v34
	v_cvt_f32_i32_e32 v35, v35
	v_cvt_f32_i32_e32 v36, v36
	v_cvt_f32_i32_e32 v37, v37
	v_pk_mul_f32 v[78:79], v[78:79], v[216:217]
	v_pk_mul_f32 v[80:81], v[80:81], v[218:219]
	v_pk_mul_f32 v[74:75], v[74:75], v[224:225]
	v_pk_mul_f32 v[76:77], v[76:77], v[226:227]
	v_pk_mul_f32 v[248:249], v[78:79], v[238:239] op_sel_hi:[1,0]
	v_pk_mul_f32 v[250:251], v[80:81], v[238:239] op_sel_hi:[1,0]
	v_pk_mul_f32 v[78:79], v[78:79], v[74:75]
	v_exp_f32_e32 v248, v248
	v_exp_f32_e32 v249, v249
	v_exp_f32_e32 v250, v250
	v_exp_f32_e32 v251, v251
	v_pk_mul_f32 v[80:81], v[80:81], v[76:77]
	v_pk_fma_f32 v[248:249], v[248:249], v[238:239], v[238:239] op_sel:[0,1,1] op_sel_hi:[1,1,1]
; __device__ __forceinline__ float silu_f(float x) { return x * __builtin_amdgcn_rcpf(1.0f + __builtin_amdgcn_exp2f(-1.4426950408889634f * x)); }
;     __device__ __forceinline__ void operator()(const i32x4 (&acc)[2][2][4][2], const pg8::Unit& u, int wr, int wc, int fr_, int fq_, int tid) {
;     ...
;         for (int ai = 0; ai < 2; ++ai)
; #pragma unroll
;             for (int m = 0; m < 4; ++m) {
;                 const int row = row0 + ai * 128 + m * 16;
;                 const float rs = rsl[wr * 64 + fr + ai * 128 + m * 16];
;                 f32x4 h[2];
; #pragma unroll
;                 for (int n = 0; n < 2; ++n) {
; #pragma unroll
;                     for (int i = 0; i < 4; ++i) { const float g = (float)acc[ai][0][m][n][i] * (rs * cs[0][n][i]), up = (float)acc[ai][1][m][n][i] * (rs * cs[1][n][i]); h[n][i] = silu_f(g) * up; } }
;                 *(u32x4*)(H + ((size_t)(u.pm * (DFF / 64) + (col0 >> 6)) * 256 + (size_t)(row & 255)) * 64 + (col0 & 63)) = pack8bf(h[0], h[1]);
	v_pk_fma_f32 v[250:251], v[250:251], v[238:239], v[238:239] op_sel:[0,1,1] op_sel_hi:[1,1,1]
	v_rcp_f32_e32 v248, v248
	v_rcp_f32_e32 v249, v249
	v_rcp_f32_e32 v250, v250
	v_rcp_f32_e32 v251, v251
	v_pk_mul_f32 v[78:79], v[78:79], v[248:249]
	v_pk_mul_f32 v[80:81], v[80:81], v[250:251]
	v_cvt_pk_bf16_f32 v74, v78, v79
	v_cvt_pk_bf16_f32 v75, v80, v81
	v_pk_mul_f32 v[70:71], v[70:71], v[220:221]
	v_pk_mul_f32 v[72:73], v[72:73], v[222:223]
	v_pk_mul_f32 v[66:67], v[66:67], v[228:229]
	v_pk_mul_f32 v[68:69], v[68:69], v[230:231]
	v_pk_mul_f32 v[248:249], v[70:71], v[238:239] op_sel_hi:[1,0]
	v_pk_mul_f32 v[250:251], v[72:73], v[238:239] op_sel_hi:[1,0]
	v_pk_mul_f32 v[70:71], v[70:71], v[66:67]
	v_exp_f32_e32 v248, v248
	v_exp_f32_e32 v249, v249
	v_exp_f32_e32 v250, v250
	v_exp_f32_e32 v251, v251
	v_pk_mul_f32 v[72:73], v[72:73], v[68:69]
	v_pk_fma_f32 v[248:249], v[248:249], v[238:239], v[238:239] op_sel:[0,1,1] op_sel_hi:[1,1,1]
	v_pk_fma_f32 v[250:251], v[250:251], v[238:239], v[238:239] op_sel:[0,1,1] op_sel_hi:[1,1,1]
	v_rcp_f32_e32 v248, v248
	v_rcp_f32_e32 v249, v249
	v_rcp_f32_e32 v250, v250
	v_rcp_f32_e32 v251, v251
	v_pk_mul_f32 v[70:71], v[70:71], v[248:249]
	v_pk_mul_f32 v[72:73], v[72:73], v[250:251]
	v_cvt_pk_bf16_f32 v76, v70, v71
	v_cvt_pk_bf16_f32 v77, v72, v73
	global_store_dwordx4 v176, v[74:77], s[22:23] offset:2048 sc1 nt
	v_cvt_f32_i32_e32 v30, v30
	v_cvt_f32_i32_e32 v31, v31
	v_cvt_f32_i32_e32 v32, v32
	v_cvt_f32_i32_e32 v33, v33
	v_cvt_f32_i32_e32 v26, v26
	v_cvt_f32_i32_e32 v27, v27
	v_cvt_f32_i32_e32 v28, v28
	v_cvt_f32_i32_e32 v29, v29
	v_cvt_f32_i32_e32 v22, v22
	v_cvt_f32_i32_e32 v23, v23
	v_cvt_f32_i32_e32 v24, v24
	v_cvt_f32_i32_e32 v25, v25
	v_cvt_f32_i32_e32 v18, v18
	v_cvt_f32_i32_e32 v19, v19
	v_cvt_f32_i32_e32 v20, v20
	v_cvt_f32_i32_e32 v21, v21
	v_pk_mul_f32 v[62:63], v[62:63], v[216:217]
	v_pk_mul_f32 v[64:65], v[64:65], v[218:219]
	v_pk_mul_f32 v[58:59], v[58:59], v[224:225]
	v_pk_mul_f32 v[60:61], v[60:61], v[226:227]
	v_pk_mul_f32 v[248:249], v[62:63], v[240:241] op_sel_hi:[1,0]
	v_pk_mul_f32 v[250:251], v[64:65], v[240:241] op_sel_hi:[1,0]
	v_pk_mul_f32 v[62:63], v[62:63], v[58:59]
	v_exp_f32_e32 v248, v248
	v_exp_f32_e32 v249, v249
	v_exp_f32_e32 v250, v250
	v_exp_f32_e32 v251, v251
	v_pk_mul_f32 v[64:65], v[64:65], v[60:61]
	v_pk_fma_f32 v[248:249], v[248:249], v[240:241], v[240:241] op_sel:[0,1,1] op_sel_hi:[1,1,1]
	v_pk_fma_f32 v[250:251], v[250:251], v[240:241], v[240:241] op_sel:[0,1,1] op_sel_hi:[1,1,1]
	v_rcp_f32_e32 v248, v248
	v_rcp_f32_e32 v249, v249
	v_rcp_f32_e32 v250, v250
	v_rcp_f32_e32 v251, v251
	v_pk_mul_f32 v[62:63], v[62:63], v[248:249]
	v_pk_mul_f32 v[64:65], v[64:65], v[250:251]
	v_cvt_pk_bf16_f32 v58, v62, v63
	v_cvt_pk_bf16_f32 v59, v64, v65
	v_pk_mul_f32 v[54:55], v[54:55], v[220:221]
	v_pk_mul_f32 v[56:57], v[56:57], v[222:223]
	v_pk_mul_f32 v[50:51], v[50:51], v[228:229]
	v_pk_mul_f32 v[52:53], v[52:53], v[230:231]
	v_pk_mul_f32 v[248:249], v[54:55], v[240:241] op_sel_hi:[1,0]
	v_pk_mul_f32 v[250:251], v[56:57], v[240:241] op_sel_hi:[1,0]
	v_pk_mul_f32 v[54:55], v[54:55], v[50:51]
	v_exp_f32_e32 v248, v248
	v_exp_f32_e32 v249, v249
	v_exp_f32_e32 v250, v250
	v_exp_f32_e32 v251, v251
	v_pk_mul_f32 v[56:57], v[56:57], v[52:53]
	v_pk_fma_f32 v[248:249], v[248:249], v[240:241], v[240:241] op_sel:[0,1,1] op_sel_hi:[1,1,1]
	v_pk_fma_f32 v[250:251], v[250:251], v[240:241], v[240:241] op_sel:[0,1,1] op_sel_hi:[1,1,1]
	v_rcp_f32_e32 v248, v248
	v_rcp_f32_e32 v249, v249
	v_rcp_f32_e32 v250, v250
	v_rcp_f32_e32 v251, v251
	v_pk_mul_f32 v[54:55], v[54:55], v[248:249]
	v_pk_mul_f32 v[56:57], v[56:57], v[250:251]
	v_cvt_pk_bf16_f32 v60, v54, v55
	v_cvt_pk_bf16_f32 v61, v56, v57
	s_add_u32 s22, s20, 0x4000
	s_addc_u32 s23, s21, 0
	global_store_dwordx4 v176, v[58:61], s[22:23] sc1 nt
	v_cvt_f32_i32_e32 v14, v14
	v_cvt_f32_i32_e32 v15, v15
	v_cvt_f32_i32_e32 v16, v16
	v_cvt_f32_i32_e32 v17, v17
	v_cvt_f32_i32_e32 v10, v10
	v_cvt_f32_i32_e32 v11, v11
	v_cvt_f32_i32_e32 v12, v12
	v_cvt_f32_i32_e32 v13, v13
	v_cvt_f32_i32_e32 v6, v6
	v_cvt_f32_i32_e32 v7, v7
	v_cvt_f32_i32_e32 v8, v8
	v_cvt_f32_i32_e32 v9, v9
	v_cvt_f32_i32_e32 v2, v2
	v_cvt_f32_i32_e32 v3, v3
	v_cvt_f32_i32_e32 v4, v4
	v_cvt_f32_i32_e32 v5, v5
	v_pk_mul_f32 v[46:47], v[46:47], v[216:217]
	v_pk_mul_f32 v[48:49], v[48:49], v[218:219]
	v_pk_mul_f32 v[42:43], v[42:43], v[224:225]
	v_pk_mul_f32 v[44:45], v[44:45], v[226:227]
	v_pk_mul_f32 v[248:249], v[46:47], v[242:243] op_sel_hi:[1,0]
	v_pk_mul_f32 v[250:251], v[48:49], v[242:243] op_sel_hi:[1,0]
	v_pk_mul_f32 v[46:47], v[46:47], v[42:43]
	v_exp_f32_e32 v248, v248
	v_exp_f32_e32 v249, v249
	v_exp_f32_e32 v250, v250
	v_exp_f32_e32 v251, v251
	v_pk_mul_f32 v[48:49], v[48:49], v[44:45]
	v_pk_fma_f32 v[248:249], v[248:249], v[242:243], v[242:243] op_sel:[0,1,1] op_sel_hi:[1,1,1]
	v_pk_fma_f32 v[250:251], v[250:251], v[242:243], v[242:243] op_sel:[0,1,1] op_sel_hi:[1,1,1]
	v_rcp_f32_e32 v248, v248
	v_rcp_f32_e32 v249, v249
	v_rcp_f32_e32 v250, v250
	v_rcp_f32_e32 v251, v251
	v_pk_mul_f32 v[46:47], v[46:47], v[248:249]
	v_pk_mul_f32 v[48:49], v[48:49], v[250:251]
	v_cvt_pk_bf16_f32 v42, v46, v47
; __device__ __forceinline__ float silu_f(float x) { return x * __builtin_amdgcn_rcpf(1.0f + __builtin_amdgcn_exp2f(-1.4426950408889634f * x)); }
; #define PG8_BAR __builtin_amdgcn_s_barrier()
;     ...
;         E(acc, cur, wr, wc, fr, fq, tid); S.done(cur);
;         if (!has_next) break;
; #pragma unroll
;         for (int a = 0; a < 2; ++a)
; #pragma unroll
;             for (int b = 0; b < 2; ++b)
; #pragma unroll
;                 for (int m = 0; m < 4; ++m)
; #pragma unroll
;                     for (int n = 0; n < 2; ++n) acc[a][b][m][n] = acc_t{};
;         cur = nxt; cA = nA; cB = nB; ++ui;
;         if constexpr (ALIGN_EPI) { if (wr == 1) PG8_BAR; }
;     __device__ __forceinline__ void operator()(const i32x4 (&acc)[2][2][4][2], const pg8::Unit& u, int wr, int wc, int fr_, int fq_, int tid) {
;     ...
;         for (int ai = 0; ai < 2; ++ai)
; #pragma unroll
;             for (int m = 0; m < 4; ++m) {
;                 const int row = row0 + ai * 128 + m * 16;
;                 const float rs = rsl[wr * 64 + fr + ai * 128 + m * 16];
;                 f32x4 h[2];
; #pragma unroll
;                 for (int n = 0; n < 2; ++n) {
; #pragma unroll
;                     for (int i = 0; i < 4; ++i) { const float g = (float)acc[ai][0][m][n][i] * (rs * cs[0][n][i]), up = (float)acc[ai][1][m][n][i] * (rs * cs[1][n][i]); h[n][i] = silu_f(g) * up; } }
;                 *(u32x4*)(H + ((size_t)(u.pm * (DFF / 64) + (col0 >> 6)) * 256 + (size_t)(row & 255)) * 64 + (col0 & 63)) = pack8bf(h[0], h[1]);
	v_cvt_pk_bf16_f32 v43, v48, v49
	v_pk_mul_f32 v[38:39], v[38:39], v[220:221]
	v_pk_mul_f32 v[40:41], v[40:41], v[222:223]
	v_pk_mul_f32 v[34:35], v[34:35], v[228:229]
	v_pk_mul_f32 v[36:37], v[36:37], v[230:231]
	v_pk_mul_f32 v[248:249], v[38:39], v[242:243] op_sel_hi:[1,0]
	v_pk_mul_f32 v[250:251], v[40:41], v[242:243] op_sel_hi:[1,0]
	v_pk_mul_f32 v[38:39], v[38:39], v[34:35]
	v_exp_f32_e32 v248, v248
	v_exp_f32_e32 v249, v249
	v_exp_f32_e32 v250, v250
	v_exp_f32_e32 v251, v251
	v_pk_mul_f32 v[40:41], v[40:41], v[36:37]
	v_pk_fma_f32 v[248:249], v[248:249], v[242:243], v[242:243] op_sel:[0,1,1] op_sel_hi:[1,1,1]
	v_pk_fma_f32 v[250:251], v[250:251], v[242:243], v[242:243] op_sel:[0,1,1] op_sel_hi:[1,1,1]
	v_rcp_f32_e32 v248, v248
	v_rcp_f32_e32 v249, v249
	v_rcp_f32_e32 v250, v250
	v_rcp_f32_e32 v251, v251
	v_pk_mul_f32 v[38:39], v[38:39], v[248:249]
	v_pk_mul_f32 v[40:41], v[40:41], v[250:251]
	v_cvt_pk_bf16_f32 v44, v38, v39
	v_cvt_pk_bf16_f32 v45, v40, v41
	global_store_dwordx4 v176, v[42:45], s[22:23] offset:2048 sc1 nt
	v_pk_mul_f32 v[30:31], v[30:31], v[216:217]
	v_pk_mul_f32 v[32:33], v[32:33], v[218:219]
	v_pk_mul_f32 v[26:27], v[26:27], v[224:225]
	v_pk_mul_f32 v[28:29], v[28:29], v[226:227]
	v_pk_mul_f32 v[248:249], v[30:31], v[244:245] op_sel_hi:[1,0]
	v_pk_mul_f32 v[250:251], v[32:33], v[244:245] op_sel_hi:[1,0]
	v_pk_mul_f32 v[30:31], v[30:31], v[26:27]
	v_exp_f32_e32 v248, v248
	v_exp_f32_e32 v249, v249
	v_exp_f32_e32 v250, v250
	v_exp_f32_e32 v251, v251
	v_pk_mul_f32 v[32:33], v[32:33], v[28:29]
	v_pk_fma_f32 v[248:249], v[248:249], v[244:245], v[244:245] op_sel:[0,1,1] op_sel_hi:[1,1,1]
	v_pk_fma_f32 v[250:251], v[250:251], v[244:245], v[244:245] op_sel:[0,1,1] op_sel_hi:[1,1,1]
	v_rcp_f32_e32 v248, v248
	v_rcp_f32_e32 v249, v249
	v_rcp_f32_e32 v250, v250
	v_rcp_f32_e32 v251, v251
	v_pk_mul_f32 v[30:31], v[30:31], v[248:249]
	v_pk_mul_f32 v[32:33], v[32:33], v[250:251]
	v_cvt_pk_bf16_f32 v26, v30, v31
	v_cvt_pk_bf16_f32 v27, v32, v33
	v_pk_mul_f32 v[22:23], v[22:23], v[220:221]
	v_pk_mul_f32 v[24:25], v[24:25], v[222:223]
	v_pk_mul_f32 v[18:19], v[18:19], v[228:229]
	v_pk_mul_f32 v[20:21], v[20:21], v[230:231]
	v_pk_mul_f32 v[248:249], v[22:23], v[244:245] op_sel_hi:[1,0]
	v_pk_mul_f32 v[250:251], v[24:25], v[244:245] op_sel_hi:[1,0]
	v_pk_mul_f32 v[22:23], v[22:23], v[18:19]
	v_exp_f32_e32 v248, v248
	v_exp_f32_e32 v249, v249
	v_exp_f32_e32 v250, v250
	v_exp_f32_e32 v251, v251
	v_pk_mul_f32 v[24:25], v[24:25], v[20:21]
	v_pk_fma_f32 v[248:249], v[248:249], v[244:245], v[244:245] op_sel:[0,1,1] op_sel_hi:[1,1,1]
	v_pk_fma_f32 v[250:251], v[250:251], v[244:245], v[244:245] op_sel:[0,1,1] op_sel_hi:[1,1,1]
	v_rcp_f32_e32 v248, v248
	v_rcp_f32_e32 v249, v249
	v_rcp_f32_e32 v250, v250
	v_rcp_f32_e32 v251, v251
	v_pk_mul_f32 v[22:23], v[22:23], v[248:249]
	v_pk_mul_f32 v[24:25], v[24:25], v[250:251]
	v_cvt_pk_bf16_f32 v28, v22, v23
	v_cvt_pk_bf16_f32 v29, v24, v25
	s_add_u32 s22, s20, 0x5000
	s_addc_u32 s23, s21, 0
	global_store_dwordx4 v176, v[26:29], s[22:23] sc1 nt
	v_pk_mul_f32 v[14:15], v[14:15], v[216:217]
	v_pk_mul_f32 v[16:17], v[16:17], v[218:219]
	v_pk_mul_f32 v[10:11], v[10:11], v[224:225]
	v_pk_mul_f32 v[12:13], v[12:13], v[226:227]
	v_pk_mul_f32 v[248:249], v[14:15], v[246:247] op_sel_hi:[1,0]
	v_pk_mul_f32 v[250:251], v[16:17], v[246:247] op_sel_hi:[1,0]
	v_pk_mul_f32 v[14:15], v[14:15], v[10:11]
	v_exp_f32_e32 v248, v248
	v_exp_f32_e32 v249, v249
	v_exp_f32_e32 v250, v250
	v_exp_f32_e32 v251, v251
	v_pk_mul_f32 v[16:17], v[16:17], v[12:13]
	v_pk_fma_f32 v[248:249], v[248:249], v[246:247], v[246:247] op_sel:[0,1,1] op_sel_hi:[1,1,1]
	v_pk_fma_f32 v[250:251], v[250:251], v[246:247], v[246:247] op_sel:[0,1,1] op_sel_hi:[1,1,1]
	v_rcp_f32_e32 v248, v248
	v_rcp_f32_e32 v249, v249
	v_rcp_f32_e32 v250, v250
	v_rcp_f32_e32 v251, v251
	v_pk_mul_f32 v[14:15], v[14:15], v[248:249]
	v_pk_mul_f32 v[16:17], v[16:17], v[250:251]
	v_cvt_pk_bf16_f32 v10, v14, v15
	v_cvt_pk_bf16_f32 v11, v16, v17
	v_pk_mul_f32 v[6:7], v[6:7], v[220:221]
	v_pk_mul_f32 v[8:9], v[8:9], v[222:223]
	v_pk_mul_f32 v[2:3], v[2:3], v[228:229]
	v_pk_mul_f32 v[4:5], v[4:5], v[230:231]
	v_pk_mul_f32 v[248:249], v[6:7], v[246:247] op_sel_hi:[1,0]
	v_pk_mul_f32 v[250:251], v[8:9], v[246:247] op_sel_hi:[1,0]
	v_pk_mul_f32 v[6:7], v[6:7], v[2:3]
	v_exp_f32_e32 v248, v248
	v_exp_f32_e32 v249, v249
	v_exp_f32_e32 v250, v250
	v_exp_f32_e32 v251, v251
	v_pk_mul_f32 v[8:9], v[8:9], v[4:5]
	v_pk_fma_f32 v[248:249], v[248:249], v[246:247], v[246:247] op_sel:[0,1,1] op_sel_hi:[1,1,1]
	v_pk_fma_f32 v[250:251], v[250:251], v[246:247], v[246:247] op_sel:[0,1,1] op_sel_hi:[1,1,1]
	v_rcp_f32_e32 v248, v248
	v_rcp_f32_e32 v249, v249
	v_rcp_f32_e32 v250, v250
	v_rcp_f32_e32 v251, v251
	v_pk_mul_f32 v[6:7], v[6:7], v[248:249]
	v_pk_mul_f32 v[8:9], v[8:9], v[250:251]
	v_cvt_pk_bf16_f32 v12, v6, v7
	v_cvt_pk_bf16_f32 v13, v8, v9
	global_store_dwordx4 v176, v[10:13], s[22:23] offset:2048 sc1 nt
	s_mov_b64 s[20:21], -1
	s_andn2_b64 vcc, exec, s[4:5]
	s_cbranch_vccnz .LBB0_159
	s_andn2_b64 vcc, exec, s[6:7]
	s_cbranch_vccnz .LBB0_158
	s_barrier
	s_branch .LBB0_158
